# P4: upper-half blocks run the scan item before the attention item (overlap latency-bound scan with the co-resident block's attention)
# speedup vs baseline: 1.0105x; 1.0105x over previous
.LBB0_734:
	s_or_b64 exec, exec, s[0:1]
	v_readlane_b32 s0, v254, 17
	v_readlane_b32 s1, v254, 18
	s_andn2_b64 vcc, exec, s[0:1]
	v_readlane_b32 s2, v255, 21
	v_readlane_b32 s5, v252, 0
	s_mov_b32 s98, s50
	s_cmpk_lg_i32 s50, 0x200
	s_cbranch_scc1 .Lp4_noswap
	s_cmpk_lt_i32 s5, 0x100
	s_cbranch_scc1 .Lp4_noswap
	s_addk_i32 s5, 0x200
	s_lshl_b32 s2, s5, 8
	s_sub_i32 s98, 0, s50
.Lp4_noswap:
	s_waitcnt lgkmcnt(0)
	s_barrier
	s_cbranch_vccz .LBB0_740

.LBB0_739:
	s_add_i32 s5, s5, s98
	s_lshl_b32 s2, s5, 8
	s_cmp_gt_u32 s5, 0x3ff
	s_cbranch_scc1 .LBB0_735
